# grid barrier: non-leader workgroups spin on the top-level generation word directly; per-XCD generation bump removed
# speedup vs baseline: 1.0068x; 1.0068x over previous
.LBB0_136:
	s_or_b64 exec, exec, s[8:9]
	v_cvt_f32_u32_e32 v4, v2
	s_waitcnt vmcnt(0)
	v_readfirstlane_b32 s6, v3
	v_sub_u32_e32 v3, 0, v2
	v_rcp_iflag_f32_e32 v4, v4
	v_add_u32_e32 v5, s6, v1
	v_mul_f32_e32 v4, 0x4f7ffffe, v4
	v_cvt_u32_f32_e32 v4, v4
	v_mul_lo_u32 v1, v3, v4
	v_mul_hi_u32 v1, v4, v1
	v_add_u32_e32 v1, v4, v1
	v_mul_hi_u32 v1, v5, v1
	v_mul_lo_u32 v3, v1, v2
	v_sub_u32_e32 v3, v5, v3
	v_add_u32_e32 v4, 1, v1
	v_cmp_ge_u32_e32 vcc, v3, v2
	s_nop 1
	v_cndmask_b32_e32 v1, v1, v4, vcc
	v_sub_u32_e32 v4, v3, v2
	v_cndmask_b32_e32 v3, v3, v4, vcc
	v_add_u32_e32 v4, 1, v1
	v_cmp_ge_u32_e32 vcc, v3, v2
	v_add_u32_e32 v3, 1, v5
	s_nop 0
	v_cndmask_b32_e32 v1, v1, v4, vcc
	v_mul_lo_u32 v4, v2, v1
	v_add_u32_e32 v2, v4, v2
	v_cmp_ne_u32_e32 vcc, v3, v2
	s_and_saveexec_b64 s[6:7], vcc
	s_xor_b64 s[6:7], exec, s[6:7]
	s_cbranch_execz .LBB0_151
	s_waitcnt lgkmcnt(0)
	s_add_u32 s12, s2, 0x31c3500
	s_addc_u32 s13, s3, 0
	v_mov_b32_e32 v0, 0
	global_load_dword v0, v0, s[12:13] sc1
	s_waitcnt vmcnt(0)
	v_cmp_eq_u32_e32 vcc, v0, v1
	s_and_saveexec_b64 s[8:9], vcc
	s_cbranch_execz .LBB0_150
	s_add_u32 s10, s2, 0x31c0200
	s_addc_u32 s11, s3, 0
	s_mov_b32 s24, 1
	s_mov_b64 s[14:15], 0
	v_mov_b32_e32 v0, 0
	s_branch .LBB0_140

.LBB0_170:
	s_or_b64 exec, exec, s[2:3]
	s_mov_b64 s[2:3], exec
	v_mbcnt_lo_u32_b32 v0, s2, 0
	v_mbcnt_hi_u32_b32 v0, s3, v0
	v_cmp_eq_u32_e32 vcc, 0, v0
	s_waitcnt vmcnt(0)
	buffer_inv sc1
	s_and_saveexec_b64 s[6:7], vcc
	s_cbranch_execz .LBB0_172
	s_bcnt1_i32_b64 s2, s[2:3]
	v_mov_b32_e32 v0, 0x2000
	v_mov_b32_e32 v1, s2
	s_nop 0

.LBB0_256:
	s_or_b64 exec, exec, s[10:11]
	v_cvt_f32_u32_e32 v5, v3
	s_waitcnt vmcnt(0)
	v_readfirstlane_b32 s8, v4
	v_sub_u32_e32 v4, 0, v3
	v_rcp_iflag_f32_e32 v5, v5
	v_add_u32_e32 v6, s8, v1
	v_mul_f32_e32 v5, 0x4f7ffffe, v5
	v_cvt_u32_f32_e32 v5, v5
	v_mul_lo_u32 v1, v4, v5
	v_mul_hi_u32 v1, v5, v1
	v_add_u32_e32 v1, v5, v1
	v_mul_hi_u32 v1, v6, v1
	v_mul_lo_u32 v4, v1, v3
	v_sub_u32_e32 v4, v6, v4
	v_add_u32_e32 v5, 1, v1
	v_cmp_ge_u32_e32 vcc, v4, v3
	s_nop 1
	v_cndmask_b32_e32 v1, v1, v5, vcc
	v_sub_u32_e32 v5, v4, v3
	v_cndmask_b32_e32 v4, v4, v5, vcc
	v_add_u32_e32 v5, 1, v1
	v_cmp_ge_u32_e32 vcc, v4, v3
	v_add_u32_e32 v4, 1, v6
	s_nop 0
	v_cndmask_b32_e32 v1, v1, v5, vcc
	v_mul_lo_u32 v5, v3, v1
	v_add_u32_e32 v3, v5, v3
	v_cmp_ne_u32_e32 vcc, v4, v3
	s_and_saveexec_b64 s[8:9], vcc
	s_xor_b64 s[8:9], exec, s[8:9]
	s_cbranch_execz .LBB0_270
	s_waitcnt lgkmcnt(0)
	s_add_u32 s14, s4, 0x31c3500
	s_addc_u32 s15, s5, 0
	v_mov_b32_e32 v2, 0
	global_load_dword v2, v2, s[14:15] sc1
	s_waitcnt vmcnt(0)
	v_cmp_eq_u32_e32 vcc, v2, v1
	s_and_saveexec_b64 s[10:11], vcc
	s_cbranch_execz .LBB0_269
	s_add_u32 s12, s4, 0x31c0200
	s_addc_u32 s13, s5, 0
	s_mov_b32 s28, 1
	s_mov_b64 s[18:19], 0
	s_branch .LBB0_260

.LBB0_287:
	s_or_b64 exec, exec, s[4:5]
	s_mov_b64 s[4:5], exec
	v_mbcnt_lo_u32_b32 v1, s4, 0
	v_mbcnt_hi_u32_b32 v1, s5, v1
	v_cmp_eq_u32_e32 vcc, 0, v1
	s_waitcnt vmcnt(0)
	buffer_inv sc1
	s_and_saveexec_b64 s[8:9], vcc
	s_cbranch_execz .LBB0_289
	s_bcnt1_i32_b64 s4, s[4:5]
	v_mov_b32_e32 v1, s4
	v_mov_b32_e32 v2, 0x2000
	s_nop 0

.LBB0_320:
	s_or_b64 exec, exec, s[12:13]
	v_cvt_f32_u32_e32 v5, v3
	s_waitcnt vmcnt(0)
	v_readfirstlane_b32 s8, v4
	v_sub_u32_e32 v4, 0, v3
	v_rcp_iflag_f32_e32 v5, v5
	v_add_u32_e32 v6, s8, v1
	v_mul_f32_e32 v5, 0x4f7ffffe, v5
	v_cvt_u32_f32_e32 v5, v5
	v_mul_lo_u32 v1, v4, v5
	v_mul_hi_u32 v1, v5, v1
	v_add_u32_e32 v1, v5, v1
	v_mul_hi_u32 v1, v6, v1
	v_mul_lo_u32 v4, v1, v3
	v_sub_u32_e32 v4, v6, v4
	v_add_u32_e32 v5, 1, v1
	v_cmp_ge_u32_e32 vcc, v4, v3
	s_nop 1
	v_cndmask_b32_e32 v1, v1, v5, vcc
	v_sub_u32_e32 v5, v4, v3
	v_cndmask_b32_e32 v4, v4, v5, vcc
	v_add_u32_e32 v5, 1, v1
	v_cmp_ge_u32_e32 vcc, v4, v3
	v_add_u32_e32 v4, 1, v6
	s_nop 0
	v_cndmask_b32_e32 v1, v1, v5, vcc
	v_mul_lo_u32 v5, v3, v1
	v_add_u32_e32 v3, v5, v3
	v_cmp_ne_u32_e32 vcc, v4, v3
	s_and_saveexec_b64 s[8:9], vcc
	s_xor_b64 s[8:9], exec, s[8:9]
	s_cbranch_execz .LBB0_334
	s_waitcnt lgkmcnt(0)
	s_add_u32 s18, s4, 0x31c3500
	s_addc_u32 s19, s5, 0
	v_mov_b32_e32 v2, 0
	global_load_dword v2, v2, s[18:19] sc1
	s_waitcnt vmcnt(0)
	v_cmp_eq_u32_e32 vcc, v2, v1
	s_and_saveexec_b64 s[12:13], vcc
	s_cbranch_execz .LBB0_333
	s_add_u32 s14, s4, 0x31c0200
	s_addc_u32 s15, s5, 0
	s_mov_b32 s30, 1
	s_mov_b64 s[20:21], 0
	s_branch .LBB0_324

.LBB0_423:
	s_or_b64 exec, exec, s[12:13]
	v_cvt_f32_u32_e32 v5, v3
	s_waitcnt vmcnt(0)
	v_readfirstlane_b32 s8, v4
	v_sub_u32_e32 v4, 0, v3
	v_rcp_iflag_f32_e32 v5, v5
	v_add_u32_e32 v6, s8, v1
	v_mul_f32_e32 v5, 0x4f7ffffe, v5
	v_cvt_u32_f32_e32 v5, v5
	v_mul_lo_u32 v1, v4, v5
	v_mul_hi_u32 v1, v5, v1
	v_add_u32_e32 v1, v5, v1
	v_mul_hi_u32 v1, v6, v1
	v_mul_lo_u32 v4, v1, v3
	v_sub_u32_e32 v4, v6, v4
	v_add_u32_e32 v5, 1, v1
	v_cmp_ge_u32_e32 vcc, v4, v3
	s_nop 1
	v_cndmask_b32_e32 v1, v1, v5, vcc
	v_sub_u32_e32 v5, v4, v3
	v_cndmask_b32_e32 v4, v4, v5, vcc
	v_add_u32_e32 v5, 1, v1
	v_cmp_ge_u32_e32 vcc, v4, v3
	v_add_u32_e32 v4, 1, v6
	s_nop 0
	v_cndmask_b32_e32 v1, v1, v5, vcc
	v_mul_lo_u32 v5, v3, v1
	v_add_u32_e32 v3, v5, v3
	v_cmp_ne_u32_e32 vcc, v4, v3
	s_and_saveexec_b64 s[8:9], vcc
	s_xor_b64 s[8:9], exec, s[8:9]
	s_cbranch_execz .LBB0_437
	s_waitcnt lgkmcnt(0)
	s_add_u32 s16, s4, 0x31c3500
	s_addc_u32 s17, s5, 0
	v_mov_b32_e32 v2, 0
	global_load_dword v2, v2, s[16:17] sc1
	s_waitcnt vmcnt(0)
	v_cmp_eq_u32_e32 vcc, v2, v1
	s_and_saveexec_b64 s[12:13], vcc
	s_cbranch_execz .LBB0_436
	s_add_u32 s14, s4, 0x31c0200
	s_addc_u32 s15, s5, 0
	s_mov_b32 s28, 1
	s_mov_b64 s[18:19], 0
	s_branch .LBB0_427

.LBB0_483:
	s_or_b64 exec, exec, s[10:11]
	v_cvt_f32_u32_e32 v5, v3
	s_waitcnt vmcnt(0)
	v_readfirstlane_b32 s8, v4
	v_sub_u32_e32 v4, 0, v3
	v_rcp_iflag_f32_e32 v5, v5
	v_add_u32_e32 v6, s8, v1
	v_mul_f32_e32 v5, 0x4f7ffffe, v5
	v_cvt_u32_f32_e32 v5, v5
	v_mul_lo_u32 v1, v4, v5
	v_mul_hi_u32 v1, v5, v1
	v_add_u32_e32 v1, v5, v1
	v_mul_hi_u32 v1, v6, v1
	v_mul_lo_u32 v4, v1, v3
	v_sub_u32_e32 v4, v6, v4
	v_add_u32_e32 v5, 1, v1
	v_cmp_ge_u32_e32 vcc, v4, v3
	s_nop 1
	v_cndmask_b32_e32 v1, v1, v5, vcc
	v_sub_u32_e32 v5, v4, v3
	v_cndmask_b32_e32 v4, v4, v5, vcc
	v_add_u32_e32 v5, 1, v1
	v_cmp_ge_u32_e32 vcc, v4, v3
	v_add_u32_e32 v4, 1, v6
	s_nop 0
	v_cndmask_b32_e32 v1, v1, v5, vcc
	v_mul_lo_u32 v5, v3, v1
	v_add_u32_e32 v3, v5, v3
	v_cmp_ne_u32_e32 vcc, v4, v3
	s_and_saveexec_b64 s[8:9], vcc
	s_xor_b64 s[8:9], exec, s[8:9]
	s_cbranch_execz .LBB0_497
	s_waitcnt lgkmcnt(0)
	s_add_u32 s14, s4, 0x31c3500
	s_addc_u32 s15, s5, 0
	v_mov_b32_e32 v2, 0
	global_load_dword v2, v2, s[14:15] sc1
	s_waitcnt vmcnt(0)
	v_cmp_eq_u32_e32 vcc, v2, v1
	s_and_saveexec_b64 s[10:11], vcc
	s_cbranch_execz .LBB0_496
	s_add_u32 s12, s4, 0x31c0200
	s_addc_u32 s13, s5, 0
	s_mov_b32 s26, 1
	s_mov_b64 s[16:17], 0
	s_branch .LBB0_487

.LBB0_555:
	s_or_b64 exec, exec, s[12:13]
	v_cvt_f32_u32_e32 v5, v3
	s_waitcnt vmcnt(0)
	v_readfirstlane_b32 s10, v4
	v_sub_u32_e32 v4, 0, v3
	v_rcp_iflag_f32_e32 v5, v5
	v_add_u32_e32 v6, s10, v1
	v_mul_f32_e32 v5, 0x4f7ffffe, v5
	v_cvt_u32_f32_e32 v5, v5
	v_mul_lo_u32 v1, v4, v5
	v_mul_hi_u32 v1, v5, v1
	v_add_u32_e32 v1, v5, v1
	v_mul_hi_u32 v1, v6, v1
	v_mul_lo_u32 v4, v1, v3
	v_sub_u32_e32 v4, v6, v4
	v_add_u32_e32 v5, 1, v1
	v_cmp_ge_u32_e32 vcc, v4, v3
	s_nop 1
	v_cndmask_b32_e32 v1, v1, v5, vcc
	v_sub_u32_e32 v5, v4, v3
	v_cndmask_b32_e32 v4, v4, v5, vcc
	v_add_u32_e32 v5, 1, v1
	v_cmp_ge_u32_e32 vcc, v4, v3
	v_add_u32_e32 v4, 1, v6
	s_nop 0
	v_cndmask_b32_e32 v1, v1, v5, vcc
	v_mul_lo_u32 v5, v3, v1
	v_add_u32_e32 v3, v5, v3
	v_cmp_ne_u32_e32 vcc, v4, v3
	s_and_saveexec_b64 s[10:11], vcc
	s_xor_b64 s[10:11], exec, s[10:11]
	s_cbranch_execz .LBB0_569
	s_waitcnt lgkmcnt(0)
	s_add_u32 s16, s6, 0x31c3500
	s_addc_u32 s17, s7, 0
	v_mov_b32_e32 v2, 0
	global_load_dword v2, v2, s[16:17] sc1
	s_waitcnt vmcnt(0)
	v_cmp_eq_u32_e32 vcc, v2, v1
	s_and_saveexec_b64 s[12:13], vcc
	s_cbranch_execz .LBB0_568
	s_add_u32 s14, s6, 0x31c0200
	s_addc_u32 s15, s7, 0
	s_mov_b32 s28, 1
	s_mov_b64 s[18:19], 0
	s_branch .LBB0_559

.LBB0_586:
	s_or_b64 exec, exec, s[6:7]
	s_mov_b64 s[6:7], exec
	v_mbcnt_lo_u32_b32 v1, s6, 0
	v_mbcnt_hi_u32_b32 v1, s7, v1
	v_cmp_eq_u32_e32 vcc, 0, v1
	s_waitcnt vmcnt(0)
	buffer_inv sc1
	s_and_saveexec_b64 s[10:11], vcc
	s_cbranch_execz .LBB0_588
	s_bcnt1_i32_b64 s6, s[6:7]
	v_mov_b32_e32 v1, s6
	v_mov_b32_e32 v2, 0x2000
	s_nop 0

.LBB0_1463:
	s_bcnt1_i32_b64 s4, s[4:5]
	v_mov_b32_e32 v1, s4
	v_mov_b32_e32 v2, 0x2000
	s_nop 0
	s_getpc_b64 s[98:99]
